# sliding-window attention (A layers): QK^T K-fragment LDS reads issued 4 ahead through a 5-register ring using the idle K/V staging registers (counted lgkmcnt), on top of the diff-attention epilogue re
# baseline (speedup 1.0000x reference)
.LBB0_986:
	s_add_i32 s33, s39, 0xffffff80
	s_cmp_gt_i32 s33, s25
	s_cselect_b64 s[4:5], -1, 0
	s_add_i32 s41, s39, 0xffffffbf
	s_cmp_lt_i32 s41, s28
	s_cselect_b64 s[42:43], -1, 0
	s_or_b64 s[4:5], s[4:5], s[42:43]
	s_and_b64 vcc, exec, s[4:5]
	s_cbranch_vccnz .LBB0_988
	v_add_u32_e32 v17, v225, v224
	v_add_u32_e32 v22, v226, v224
	v_add_u32_e32 v23, v227, v224
	v_add_u32_e32 v24, v228, v224
	ds_read_b128 v[18:21], v17 offset:49152
	ds_read_b128 v[196:199], v17 offset:57344
	ds_read_b128 v[200:203], v22 offset:49152
	ds_read_b128 v[204:207], v22 offset:57344
	ds_read_b128 v[208:211], v23 offset:49152
	s_waitcnt vmcnt(7) lgkmcnt(4)
	v_mfma_f32_32x32x16_bf16 v[96:111], v[18:21], v[176:179], 0
	ds_read_b128 v[18:21], v23 offset:57344
	s_waitcnt lgkmcnt(4)
	v_mfma_f32_32x32x16_bf16 v[112:127], v[196:199], v[176:179], 0
	ds_read_b128 v[196:199], v24 offset:49152
	s_waitcnt vmcnt(6) lgkmcnt(4)
	v_mfma_f32_32x32x16_bf16 v[96:111], v[200:203], v[172:175], v[96:111]
	ds_read_b128 v[200:203], v24 offset:57344
	s_waitcnt lgkmcnt(4)
	v_mfma_f32_32x32x16_bf16 v[112:127], v[204:207], v[172:175], v[112:127]
	ds_read_b128 v[204:207], v17 offset:49280
	s_waitcnt vmcnt(5) lgkmcnt(4)
	v_mfma_f32_32x32x16_bf16 v[96:111], v[208:211], v[168:171], v[96:111]
	ds_read_b128 v[208:211], v17 offset:57472
	s_waitcnt lgkmcnt(4)
	v_mfma_f32_32x32x16_bf16 v[112:127], v[18:21], v[168:171], v[112:127]
	ds_read_b128 v[18:21], v22 offset:49280
	s_waitcnt vmcnt(4) lgkmcnt(4)
	v_mfma_f32_32x32x16_bf16 v[96:111], v[196:199], v[164:167], v[96:111]
	ds_read_b128 v[196:199], v22 offset:57472
	s_waitcnt lgkmcnt(4)
	v_mfma_f32_32x32x16_bf16 v[112:127], v[200:203], v[164:167], v[112:127]
	ds_read_b128 v[200:203], v23 offset:49280
	s_waitcnt vmcnt(3) lgkmcnt(4)
	v_mfma_f32_32x32x16_bf16 v[96:111], v[204:207], v[160:163], v[96:111]
	ds_read_b128 v[204:207], v23 offset:57472
	s_waitcnt lgkmcnt(4)
	v_mfma_f32_32x32x16_bf16 v[112:127], v[208:211], v[160:163], v[112:127]
	ds_read_b128 v[208:211], v24 offset:49280
	s_waitcnt vmcnt(2) lgkmcnt(4)
	v_mfma_f32_32x32x16_bf16 v[96:111], v[18:21], v[10:13], v[96:111]
	ds_read_b128 v[18:21], v24 offset:57472
	s_waitcnt lgkmcnt(4)
	v_mfma_f32_32x32x16_bf16 v[112:127], v[196:199], v[10:13], v[112:127]
	s_waitcnt vmcnt(1) lgkmcnt(3)
	v_mfma_f32_32x32x16_bf16 v[96:111], v[200:203], v[6:9], v[96:111]
	s_waitcnt lgkmcnt(2)
	v_mfma_f32_32x32x16_bf16 v[112:127], v[204:207], v[6:9], v[112:127]
	s_waitcnt vmcnt(0) lgkmcnt(1)
	v_mfma_f32_32x32x16_bf16 v[96:111], v[208:211], v[2:5], v[96:111]
	s_waitcnt lgkmcnt(0)
	v_mfma_f32_32x32x16_bf16 v[112:127], v[18:21], v[2:5], v[112:127]
	s_branch .LBB0_989

.LBB0_1001:
	s_waitcnt lgkmcnt(0)
	s_barrier
	s_cmp_gt_i32 s40, s25
	s_cselect_b64 s[42:43], -1, 0
	s_add_i32 s33, s39, -1
	s_cmp_lt_i32 s33, s28
	s_cselect_b64 s[44:45], -1, 0
	s_or_b64 s[68:69], s[42:43], s[44:45]
	s_and_b64 vcc, exec, s[68:69]
	s_cbranch_vccnz .LBB0_1003
	v_add_u32_e32 v17, v225, v224
	v_add_u32_e32 v22, v226, v224
	v_add_u32_e32 v23, v227, v224
	v_add_u32_e32 v24, v228, v224
	ds_read_b128 v[18:21], v17 offset:32768
	ds_read_b128 v[196:199], v17 offset:40960
	ds_read_b128 v[200:203], v22 offset:32768
	ds_read_b128 v[204:207], v22 offset:40960
	ds_read_b128 v[208:211], v23 offset:32768
	s_waitcnt lgkmcnt(4)
	v_mfma_f32_32x32x16_bf16 v[128:143], v[18:21], v[176:179], 0
	ds_read_b128 v[18:21], v23 offset:40960
	s_waitcnt lgkmcnt(4)
	v_mfma_f32_32x32x16_bf16 v[144:159], v[196:199], v[176:179], 0
	ds_read_b128 v[196:199], v24 offset:32768
	s_waitcnt lgkmcnt(4)
	v_mfma_f32_32x32x16_bf16 v[128:143], v[200:203], v[172:175], v[128:143]
	ds_read_b128 v[200:203], v24 offset:40960
	s_waitcnt lgkmcnt(4)
	v_mfma_f32_32x32x16_bf16 v[144:159], v[204:207], v[172:175], v[144:159]
	ds_read_b128 v[204:207], v17 offset:32896
	s_waitcnt lgkmcnt(4)
	v_mfma_f32_32x32x16_bf16 v[128:143], v[208:211], v[168:171], v[128:143]
	ds_read_b128 v[208:211], v17 offset:41088
	s_waitcnt lgkmcnt(4)
	v_mfma_f32_32x32x16_bf16 v[144:159], v[18:21], v[168:171], v[144:159]
	ds_read_b128 v[18:21], v22 offset:32896
	s_waitcnt lgkmcnt(4)
	v_mfma_f32_32x32x16_bf16 v[128:143], v[196:199], v[164:167], v[128:143]
	ds_read_b128 v[196:199], v22 offset:41088
	s_waitcnt lgkmcnt(4)
	v_mfma_f32_32x32x16_bf16 v[144:159], v[200:203], v[164:167], v[144:159]
	ds_read_b128 v[200:203], v23 offset:32896
	s_waitcnt lgkmcnt(4)
	v_mfma_f32_32x32x16_bf16 v[128:143], v[204:207], v[160:163], v[128:143]
	ds_read_b128 v[204:207], v23 offset:41088
	s_waitcnt lgkmcnt(4)
	v_mfma_f32_32x32x16_bf16 v[144:159], v[208:211], v[160:163], v[144:159]
	ds_read_b128 v[208:211], v24 offset:32896
	s_waitcnt lgkmcnt(4)
	v_mfma_f32_32x32x16_bf16 v[128:143], v[18:21], v[10:13], v[128:143]
	ds_read_b128 v[18:21], v24 offset:41088
	s_waitcnt lgkmcnt(4)
	v_mfma_f32_32x32x16_bf16 v[144:159], v[196:199], v[10:13], v[144:159]
	s_waitcnt lgkmcnt(3)
	v_mfma_f32_32x32x16_bf16 v[128:143], v[200:203], v[6:9], v[128:143]
	s_waitcnt lgkmcnt(2)
	v_mfma_f32_32x32x16_bf16 v[144:159], v[204:207], v[6:9], v[144:159]
	s_waitcnt lgkmcnt(1)
	v_mfma_f32_32x32x16_bf16 v[128:143], v[208:211], v[2:5], v[128:143]
	s_waitcnt lgkmcnt(0)
	v_mfma_f32_32x32x16_bf16 v[144:159], v[18:21], v[2:5], v[144:159]
	s_and_b64 vcc, exec, s[4:5]
	s_cbranch_vccz .LBB0_1004
	s_branch .LBB0_1005
